# GEMM2 K-loop hook software-pipelined: gate groups double-buffered in the fragment registers, next group's loads issued as each quad-pair is consumed, counted vmcnt per quad-pair (same per-element op s
# speedup vs baseline: 1.0229x; 1.0147x over previous
.LBB0_867:
	s_and_b32 s2, s97, 22
	s_cmp_lg_u32 s2, 16
	s_cselect_b64 s[2:3], -1, 0
	s_xor_b64 s[4:5], s[42:43], -1
	s_or_b64 s[2:3], s[4:5], s[2:3]
	s_and_b64 vcc, exec, s[2:3]
	s_cbranch_vccnz .LBB0_869
	s_cmp_eq_u32 s97, 16
	v_mov_b32_e32 v1, v0
	s_cselect_b32 s34, 0, 0x1000
	s_addk_i32 s34, 0x800
	v_add_u32_e32 v1, v1, v212
	v_lshl_add_u64 v[2:3], v[216:217], 0, s[34:35]
	v_mad_i64_i32 v[218:219], s[2:3], v1, s20, v[2:3]
	global_load_dwordx4 v[132:135], v[218:219], off offset:-2048
	global_load_dwordx4 v[136:139], v[218:219], off offset:2048
	global_load_dwordx4 v[140:143], v[218:219], off offset:-1792
	global_load_dwordx4 v[144:147], v[218:219], off offset:2304
	v_add_u32_e32 v213, 16, v1
	v_mad_i64_i32 v[218:219], s[2:3], v213, s20, v[2:3]
	global_load_dwordx4 v[148:151], v[218:219], off offset:-2048
	global_load_dwordx4 v[152:155], v[218:219], off offset:2048
	global_load_dwordx4 v[156:159], v[218:219], off offset:-1792
	global_load_dwordx4 v[160:163], v[218:219], off offset:2304
	v_add_u32_e32 v213, 32, v1
	v_mad_i64_i32 v[218:219], s[2:3], v213, s20, v[2:3]
	global_load_dwordx4 v[164:167], v[218:219], off offset:-2048
	global_load_dwordx4 v[168:171], v[218:219], off offset:2048
	global_load_dwordx4 v[172:175], v[218:219], off offset:-1792
	global_load_dwordx4 v[176:179], v[218:219], off offset:2304
	v_add_u32_e32 v213, 48, v1
	v_mad_i64_i32 v[218:219], s[2:3], v213, s20, v[2:3]
	global_load_dwordx4 v[180:183], v[218:219], off offset:-2048
	global_load_dwordx4 v[184:187], v[218:219], off offset:2048
	global_load_dwordx4 v[188:191], v[218:219], off offset:-1792
	global_load_dwordx4 v[192:195], v[218:219], off offset:2304
	s_waitcnt vmcnt(14)
	v_lshlrev_b32_e32 v244, 16, v132
	v_lshlrev_b32_e32 v245, 16, v133
	v_and_b32_e32 v132, 0xffff0000, v132
	v_and_b32_e32 v133, 0xffff0000, v133
	v_lshlrev_b32_e32 v246, 16, v136
	v_lshlrev_b32_e32 v247, 16, v137
	v_and_b32_e32 v136, 0xffff0000, v136
	v_and_b32_e32 v137, 0xffff0000, v137
	v_lshlrev_b32_e32 v248, 16, v134
	v_lshlrev_b32_e32 v249, 16, v135
	v_and_b32_e32 v134, 0xffff0000, v134
	v_and_b32_e32 v135, 0xffff0000, v135
	v_lshlrev_b32_e32 v250, 16, v138
	v_lshlrev_b32_e32 v251, 16, v139
	v_and_b32_e32 v138, 0xffff0000, v138
	v_and_b32_e32 v139, 0xffff0000, v139
	v_mul_f32_e32 v244, 0xbfb8aa3b, v244
	v_mul_f32_e32 v245, 0xbfb8aa3b, v245
	v_mul_f32_e32 v132, 0xbfb8aa3b, v132
	v_mul_f32_e32 v133, 0xbfb8aa3b, v133
	v_mul_f32_e32 v246, 0xbfb8aa3b, v246
	v_mul_f32_e32 v247, 0xbfb8aa3b, v247
	v_mul_f32_e32 v136, 0xbfb8aa3b, v136
	v_mul_f32_e32 v137, 0xbfb8aa3b, v137
	v_mul_f32_e32 v248, 0xbfb8aa3b, v248
	v_mul_f32_e32 v249, 0xbfb8aa3b, v249
	v_mul_f32_e32 v134, 0xbfb8aa3b, v134
	v_mul_f32_e32 v135, 0xbfb8aa3b, v135
	v_mul_f32_e32 v250, 0xbfb8aa3b, v250
	v_mul_f32_e32 v251, 0xbfb8aa3b, v251
	v_mul_f32_e32 v138, 0xbfb8aa3b, v138
	v_mul_f32_e32 v139, 0xbfb8aa3b, v139
	v_exp_f32_e32 v244, v244
	v_exp_f32_e32 v245, v245
	v_exp_f32_e32 v132, v132
	v_exp_f32_e32 v133, v133
	v_exp_f32_e32 v246, v246
	v_exp_f32_e32 v247, v247
	v_exp_f32_e32 v136, v136
	v_exp_f32_e32 v137, v137
	v_exp_f32_e32 v248, v248
	v_exp_f32_e32 v249, v249
	v_exp_f32_e32 v134, v134
	v_exp_f32_e32 v135, v135
	v_exp_f32_e32 v250, v250
	v_exp_f32_e32 v251, v251
	v_exp_f32_e32 v138, v138
	v_exp_f32_e32 v139, v139
	v_pk_add_f32 v[244:245], v[244:245], 1.0 op_sel_hi:[1,0]
	v_pk_add_f32 v[132:133], v[132:133], 1.0 op_sel_hi:[1,0]
	v_pk_add_f32 v[246:247], v[246:247], 1.0 op_sel_hi:[1,0]
	v_pk_add_f32 v[136:137], v[136:137], 1.0 op_sel_hi:[1,0]
	v_pk_add_f32 v[248:249], v[248:249], 1.0 op_sel_hi:[1,0]
	v_pk_add_f32 v[134:135], v[134:135], 1.0 op_sel_hi:[1,0]
	v_pk_add_f32 v[250:251], v[250:251], 1.0 op_sel_hi:[1,0]
	v_pk_add_f32 v[138:139], v[138:139], 1.0 op_sel_hi:[1,0]
	v_rcp_f32_e32 v244, v244
	v_rcp_f32_e32 v245, v245
	v_rcp_f32_e32 v132, v132
	v_rcp_f32_e32 v133, v133
	v_rcp_f32_e32 v248, v248
	v_rcp_f32_e32 v249, v249
	v_rcp_f32_e32 v134, v134
	v_rcp_f32_e32 v135, v135
	v_pk_mul_f32 v[246:247], v[246:247], v[244:245]
	v_pk_mul_f32 v[136:137], v[136:137], v[132:133]
	v_pk_mul_f32 v[250:251], v[250:251], v[248:249]
	v_pk_mul_f32 v[138:139], v[138:139], v[134:135]
	v_mul_f32_e32 v128, v128, v246
	v_mul_f32_e32 v129, v129, v136
	v_mul_f32_e32 v130, v130, v247
	v_mul_f32_e32 v131, v131, v137
	v_mul_f32_e32 v124, v124, v250
	v_mul_f32_e32 v125, v125, v138
	v_mul_f32_e32 v126, v126, v251
	v_mul_f32_e32 v127, v127, v139
	v_add_u32_e32 v213, 128, v1
	v_mad_i64_i32 v[218:219], s[2:3], v213, s20, v[2:3]
	global_load_dwordx4 v[132:135], v[218:219], off offset:-2048
	global_load_dwordx4 v[136:139], v[218:219], off offset:2048
	s_waitcnt vmcnt(14)
	v_lshlrev_b32_e32 v244, 16, v140
	v_lshlrev_b32_e32 v245, 16, v141
	v_and_b32_e32 v140, 0xffff0000, v140
	v_and_b32_e32 v141, 0xffff0000, v141
	v_lshlrev_b32_e32 v246, 16, v144
	v_lshlrev_b32_e32 v247, 16, v145
	v_and_b32_e32 v144, 0xffff0000, v144
	v_and_b32_e32 v145, 0xffff0000, v145
	v_lshlrev_b32_e32 v248, 16, v142
	v_lshlrev_b32_e32 v249, 16, v143
	v_and_b32_e32 v142, 0xffff0000, v142
	v_and_b32_e32 v143, 0xffff0000, v143
	v_lshlrev_b32_e32 v250, 16, v146
	v_lshlrev_b32_e32 v251, 16, v147
	v_and_b32_e32 v146, 0xffff0000, v146
	v_and_b32_e32 v147, 0xffff0000, v147
	v_mul_f32_e32 v244, 0xbfb8aa3b, v244
	v_mul_f32_e32 v245, 0xbfb8aa3b, v245
	v_mul_f32_e32 v140, 0xbfb8aa3b, v140
	v_mul_f32_e32 v141, 0xbfb8aa3b, v141
	v_mul_f32_e32 v246, 0xbfb8aa3b, v246
	v_mul_f32_e32 v247, 0xbfb8aa3b, v247
	v_mul_f32_e32 v144, 0xbfb8aa3b, v144
	v_mul_f32_e32 v145, 0xbfb8aa3b, v145
	v_mul_f32_e32 v248, 0xbfb8aa3b, v248
	v_mul_f32_e32 v249, 0xbfb8aa3b, v249
	v_mul_f32_e32 v142, 0xbfb8aa3b, v142
	v_mul_f32_e32 v143, 0xbfb8aa3b, v143
	v_mul_f32_e32 v250, 0xbfb8aa3b, v250
	v_mul_f32_e32 v251, 0xbfb8aa3b, v251
	v_mul_f32_e32 v146, 0xbfb8aa3b, v146
	v_mul_f32_e32 v147, 0xbfb8aa3b, v147
	v_exp_f32_e32 v244, v244
	v_exp_f32_e32 v245, v245
	v_exp_f32_e32 v140, v140
	v_exp_f32_e32 v141, v141
	v_exp_f32_e32 v246, v246
	v_exp_f32_e32 v247, v247
	v_exp_f32_e32 v144, v144
	v_exp_f32_e32 v145, v145
	v_exp_f32_e32 v248, v248
	v_exp_f32_e32 v249, v249
	v_exp_f32_e32 v142, v142
	v_exp_f32_e32 v143, v143
	v_exp_f32_e32 v250, v250
	v_exp_f32_e32 v251, v251
	v_exp_f32_e32 v146, v146
	v_exp_f32_e32 v147, v147
	v_pk_add_f32 v[244:245], v[244:245], 1.0 op_sel_hi:[1,0]
	v_pk_add_f32 v[140:141], v[140:141], 1.0 op_sel_hi:[1,0]
	v_pk_add_f32 v[246:247], v[246:247], 1.0 op_sel_hi:[1,0]
	v_pk_add_f32 v[144:145], v[144:145], 1.0 op_sel_hi:[1,0]
	v_pk_add_f32 v[248:249], v[248:249], 1.0 op_sel_hi:[1,0]
	v_pk_add_f32 v[142:143], v[142:143], 1.0 op_sel_hi:[1,0]
	v_pk_add_f32 v[250:251], v[250:251], 1.0 op_sel_hi:[1,0]
	v_pk_add_f32 v[146:147], v[146:147], 1.0 op_sel_hi:[1,0]
	v_rcp_f32_e32 v244, v244
	v_rcp_f32_e32 v245, v245
	v_rcp_f32_e32 v140, v140
	v_rcp_f32_e32 v141, v141
	v_rcp_f32_e32 v248, v248
	v_rcp_f32_e32 v249, v249
	v_rcp_f32_e32 v142, v142
	v_rcp_f32_e32 v143, v143
	v_pk_mul_f32 v[246:247], v[246:247], v[244:245]
	v_pk_mul_f32 v[144:145], v[144:145], v[140:141]
	v_pk_mul_f32 v[250:251], v[250:251], v[248:249]
	v_pk_mul_f32 v[146:147], v[146:147], v[142:143]
	v_mul_f32_e32 v120, v120, v246
	v_mul_f32_e32 v121, v121, v144
	v_mul_f32_e32 v122, v122, v247
	v_mul_f32_e32 v123, v123, v145
	v_mul_f32_e32 v116, v116, v250
	v_mul_f32_e32 v117, v117, v146
	v_mul_f32_e32 v118, v118, v251
	v_mul_f32_e32 v119, v119, v147
	global_load_dwordx4 v[140:143], v[218:219], off offset:-1792
	global_load_dwordx4 v[144:147], v[218:219], off offset:2304
	s_waitcnt vmcnt(14)
	v_lshlrev_b32_e32 v244, 16, v148
	v_lshlrev_b32_e32 v245, 16, v149
	v_and_b32_e32 v148, 0xffff0000, v148
	v_and_b32_e32 v149, 0xffff0000, v149
	v_lshlrev_b32_e32 v246, 16, v152
	v_lshlrev_b32_e32 v247, 16, v153
	v_and_b32_e32 v152, 0xffff0000, v152
	v_and_b32_e32 v153, 0xffff0000, v153
	v_lshlrev_b32_e32 v248, 16, v150
	v_lshlrev_b32_e32 v249, 16, v151
	v_and_b32_e32 v150, 0xffff0000, v150
	v_and_b32_e32 v151, 0xffff0000, v151
	v_lshlrev_b32_e32 v250, 16, v154
	v_lshlrev_b32_e32 v251, 16, v155
	v_and_b32_e32 v154, 0xffff0000, v154
	v_and_b32_e32 v155, 0xffff0000, v155
	v_mul_f32_e32 v244, 0xbfb8aa3b, v244
	v_mul_f32_e32 v245, 0xbfb8aa3b, v245
	v_mul_f32_e32 v148, 0xbfb8aa3b, v148
	v_mul_f32_e32 v149, 0xbfb8aa3b, v149
	v_mul_f32_e32 v246, 0xbfb8aa3b, v246
	v_mul_f32_e32 v247, 0xbfb8aa3b, v247
	v_mul_f32_e32 v152, 0xbfb8aa3b, v152
	v_mul_f32_e32 v153, 0xbfb8aa3b, v153
	v_mul_f32_e32 v248, 0xbfb8aa3b, v248
	v_mul_f32_e32 v249, 0xbfb8aa3b, v249
	v_mul_f32_e32 v150, 0xbfb8aa3b, v150
	v_mul_f32_e32 v151, 0xbfb8aa3b, v151
	v_mul_f32_e32 v250, 0xbfb8aa3b, v250
	v_mul_f32_e32 v251, 0xbfb8aa3b, v251
	v_mul_f32_e32 v154, 0xbfb8aa3b, v154
	v_mul_f32_e32 v155, 0xbfb8aa3b, v155
	v_exp_f32_e32 v244, v244
	v_exp_f32_e32 v245, v245
	v_exp_f32_e32 v148, v148
	v_exp_f32_e32 v149, v149
	v_exp_f32_e32 v246, v246
	v_exp_f32_e32 v247, v247
	v_exp_f32_e32 v152, v152
	v_exp_f32_e32 v153, v153
	v_exp_f32_e32 v248, v248
	v_exp_f32_e32 v249, v249
	v_exp_f32_e32 v150, v150
	v_exp_f32_e32 v151, v151
	v_exp_f32_e32 v250, v250
	v_exp_f32_e32 v251, v251
	v_exp_f32_e32 v154, v154
	v_exp_f32_e32 v155, v155
	v_pk_add_f32 v[244:245], v[244:245], 1.0 op_sel_hi:[1,0]
	v_pk_add_f32 v[148:149], v[148:149], 1.0 op_sel_hi:[1,0]
	v_pk_add_f32 v[246:247], v[246:247], 1.0 op_sel_hi:[1,0]
	v_pk_add_f32 v[152:153], v[152:153], 1.0 op_sel_hi:[1,0]
	v_pk_add_f32 v[248:249], v[248:249], 1.0 op_sel_hi:[1,0]
	v_pk_add_f32 v[150:151], v[150:151], 1.0 op_sel_hi:[1,0]
	v_pk_add_f32 v[250:251], v[250:251], 1.0 op_sel_hi:[1,0]
	v_pk_add_f32 v[154:155], v[154:155], 1.0 op_sel_hi:[1,0]
	v_rcp_f32_e32 v244, v244
	v_rcp_f32_e32 v245, v245
	v_rcp_f32_e32 v148, v148
	v_rcp_f32_e32 v149, v149
	v_rcp_f32_e32 v248, v248
	v_rcp_f32_e32 v249, v249
	v_rcp_f32_e32 v150, v150
	v_rcp_f32_e32 v151, v151
	v_pk_mul_f32 v[246:247], v[246:247], v[244:245]
	v_pk_mul_f32 v[152:153], v[152:153], v[148:149]
	v_pk_mul_f32 v[250:251], v[250:251], v[248:249]
	v_pk_mul_f32 v[154:155], v[154:155], v[150:151]
	v_mul_f32_e32 v112, v112, v246
	v_mul_f32_e32 v113, v113, v152
	v_mul_f32_e32 v114, v114, v247
	v_mul_f32_e32 v115, v115, v153
	v_mul_f32_e32 v108, v108, v250
	v_mul_f32_e32 v109, v109, v154
	v_mul_f32_e32 v110, v110, v251
	v_mul_f32_e32 v111, v111, v155
	v_add_u32_e32 v213, 144, v1
	v_mad_i64_i32 v[218:219], s[2:3], v213, s20, v[2:3]
	global_load_dwordx4 v[148:151], v[218:219], off offset:-2048
	global_load_dwordx4 v[152:155], v[218:219], off offset:2048
	s_waitcnt vmcnt(14)
	v_lshlrev_b32_e32 v244, 16, v156
	v_lshlrev_b32_e32 v245, 16, v157
	v_and_b32_e32 v156, 0xffff0000, v156
	v_and_b32_e32 v157, 0xffff0000, v157
	v_lshlrev_b32_e32 v246, 16, v160
	v_lshlrev_b32_e32 v247, 16, v161
	v_and_b32_e32 v160, 0xffff0000, v160
	v_and_b32_e32 v161, 0xffff0000, v161
	v_lshlrev_b32_e32 v248, 16, v158
	v_lshlrev_b32_e32 v249, 16, v159
	v_and_b32_e32 v158, 0xffff0000, v158
	v_and_b32_e32 v159, 0xffff0000, v159
	v_lshlrev_b32_e32 v250, 16, v162
	v_lshlrev_b32_e32 v251, 16, v163
	v_and_b32_e32 v162, 0xffff0000, v162
	v_and_b32_e32 v163, 0xffff0000, v163
	v_mul_f32_e32 v244, 0xbfb8aa3b, v244
	v_mul_f32_e32 v245, 0xbfb8aa3b, v245
	v_mul_f32_e32 v156, 0xbfb8aa3b, v156
	v_mul_f32_e32 v157, 0xbfb8aa3b, v157
	v_mul_f32_e32 v246, 0xbfb8aa3b, v246
	v_mul_f32_e32 v247, 0xbfb8aa3b, v247
	v_mul_f32_e32 v160, 0xbfb8aa3b, v160
	v_mul_f32_e32 v161, 0xbfb8aa3b, v161
	v_mul_f32_e32 v248, 0xbfb8aa3b, v248
	v_mul_f32_e32 v249, 0xbfb8aa3b, v249
	v_mul_f32_e32 v158, 0xbfb8aa3b, v158
	v_mul_f32_e32 v159, 0xbfb8aa3b, v159
	v_mul_f32_e32 v250, 0xbfb8aa3b, v250
	v_mul_f32_e32 v251, 0xbfb8aa3b, v251
	v_mul_f32_e32 v162, 0xbfb8aa3b, v162
	v_mul_f32_e32 v163, 0xbfb8aa3b, v163
	v_exp_f32_e32 v244, v244
	v_exp_f32_e32 v245, v245
	v_exp_f32_e32 v156, v156
	v_exp_f32_e32 v157, v157
	v_exp_f32_e32 v246, v246
	v_exp_f32_e32 v247, v247
	v_exp_f32_e32 v160, v160
	v_exp_f32_e32 v161, v161
	v_exp_f32_e32 v248, v248
	v_exp_f32_e32 v249, v249
	v_exp_f32_e32 v158, v158
	v_exp_f32_e32 v159, v159
	v_exp_f32_e32 v250, v250
	v_exp_f32_e32 v251, v251
	v_exp_f32_e32 v162, v162
	v_exp_f32_e32 v163, v163
	v_pk_add_f32 v[244:245], v[244:245], 1.0 op_sel_hi:[1,0]
	v_pk_add_f32 v[156:157], v[156:157], 1.0 op_sel_hi:[1,0]
	v_pk_add_f32 v[246:247], v[246:247], 1.0 op_sel_hi:[1,0]
	v_pk_add_f32 v[160:161], v[160:161], 1.0 op_sel_hi:[1,0]
	v_pk_add_f32 v[248:249], v[248:249], 1.0 op_sel_hi:[1,0]
	v_pk_add_f32 v[158:159], v[158:159], 1.0 op_sel_hi:[1,0]
	v_pk_add_f32 v[250:251], v[250:251], 1.0 op_sel_hi:[1,0]
	v_pk_add_f32 v[162:163], v[162:163], 1.0 op_sel_hi:[1,0]
	v_rcp_f32_e32 v244, v244
	v_rcp_f32_e32 v245, v245
	v_rcp_f32_e32 v156, v156
	v_rcp_f32_e32 v157, v157
	v_rcp_f32_e32 v248, v248
	v_rcp_f32_e32 v249, v249
	v_rcp_f32_e32 v158, v158
	v_rcp_f32_e32 v159, v159
	v_pk_mul_f32 v[246:247], v[246:247], v[244:245]
	v_pk_mul_f32 v[160:161], v[160:161], v[156:157]
	v_pk_mul_f32 v[250:251], v[250:251], v[248:249]
	v_pk_mul_f32 v[162:163], v[162:163], v[158:159]
	v_mul_f32_e32 v104, v104, v246
	v_mul_f32_e32 v105, v105, v160
	v_mul_f32_e32 v106, v106, v247
	v_mul_f32_e32 v107, v107, v161
	v_mul_f32_e32 v100, v100, v250
	v_mul_f32_e32 v101, v101, v162
	v_mul_f32_e32 v102, v102, v251
	v_mul_f32_e32 v103, v103, v163
	global_load_dwordx4 v[156:159], v[218:219], off offset:-1792
	global_load_dwordx4 v[160:163], v[218:219], off offset:2304
	s_waitcnt vmcnt(14)
	v_lshlrev_b32_e32 v244, 16, v164
	v_lshlrev_b32_e32 v245, 16, v165
	v_and_b32_e32 v164, 0xffff0000, v164
	v_and_b32_e32 v165, 0xffff0000, v165
	v_lshlrev_b32_e32 v246, 16, v168
	v_lshlrev_b32_e32 v247, 16, v169
	v_and_b32_e32 v168, 0xffff0000, v168
	v_and_b32_e32 v169, 0xffff0000, v169
	v_lshlrev_b32_e32 v248, 16, v166
	v_lshlrev_b32_e32 v249, 16, v167
	v_and_b32_e32 v166, 0xffff0000, v166
	v_and_b32_e32 v167, 0xffff0000, v167
	v_lshlrev_b32_e32 v250, 16, v170
	v_lshlrev_b32_e32 v251, 16, v171
	v_and_b32_e32 v170, 0xffff0000, v170
	v_and_b32_e32 v171, 0xffff0000, v171
	v_mul_f32_e32 v244, 0xbfb8aa3b, v244
	v_mul_f32_e32 v245, 0xbfb8aa3b, v245
	v_mul_f32_e32 v164, 0xbfb8aa3b, v164
	v_mul_f32_e32 v165, 0xbfb8aa3b, v165
	v_mul_f32_e32 v246, 0xbfb8aa3b, v246
	v_mul_f32_e32 v247, 0xbfb8aa3b, v247
	v_mul_f32_e32 v168, 0xbfb8aa3b, v168
	v_mul_f32_e32 v169, 0xbfb8aa3b, v169
	v_mul_f32_e32 v248, 0xbfb8aa3b, v248
	v_mul_f32_e32 v249, 0xbfb8aa3b, v249
	v_mul_f32_e32 v166, 0xbfb8aa3b, v166
	v_mul_f32_e32 v167, 0xbfb8aa3b, v167
	v_mul_f32_e32 v250, 0xbfb8aa3b, v250
	v_mul_f32_e32 v251, 0xbfb8aa3b, v251
	v_mul_f32_e32 v170, 0xbfb8aa3b, v170
	v_mul_f32_e32 v171, 0xbfb8aa3b, v171
	v_exp_f32_e32 v244, v244
	v_exp_f32_e32 v245, v245
	v_exp_f32_e32 v164, v164
	v_exp_f32_e32 v165, v165
	v_exp_f32_e32 v246, v246
	v_exp_f32_e32 v247, v247
	v_exp_f32_e32 v168, v168
	v_exp_f32_e32 v169, v169
	v_exp_f32_e32 v248, v248
	v_exp_f32_e32 v249, v249
	v_exp_f32_e32 v166, v166
	v_exp_f32_e32 v167, v167
	v_exp_f32_e32 v250, v250
	v_exp_f32_e32 v251, v251
	v_exp_f32_e32 v170, v170
	v_exp_f32_e32 v171, v171
	v_pk_add_f32 v[244:245], v[244:245], 1.0 op_sel_hi:[1,0]
	v_pk_add_f32 v[164:165], v[164:165], 1.0 op_sel_hi:[1,0]
	v_pk_add_f32 v[246:247], v[246:247], 1.0 op_sel_hi:[1,0]
	v_pk_add_f32 v[168:169], v[168:169], 1.0 op_sel_hi:[1,0]
	v_pk_add_f32 v[248:249], v[248:249], 1.0 op_sel_hi:[1,0]
	v_pk_add_f32 v[166:167], v[166:167], 1.0 op_sel_hi:[1,0]
	v_pk_add_f32 v[250:251], v[250:251], 1.0 op_sel_hi:[1,0]
	v_pk_add_f32 v[170:171], v[170:171], 1.0 op_sel_hi:[1,0]
	v_rcp_f32_e32 v244, v244
	v_rcp_f32_e32 v245, v245
	v_rcp_f32_e32 v164, v164
	v_rcp_f32_e32 v165, v165
	v_rcp_f32_e32 v248, v248
	v_rcp_f32_e32 v249, v249
	v_rcp_f32_e32 v166, v166
	v_rcp_f32_e32 v167, v167
	v_pk_mul_f32 v[246:247], v[246:247], v[244:245]
	v_pk_mul_f32 v[168:169], v[168:169], v[164:165]
	v_pk_mul_f32 v[250:251], v[250:251], v[248:249]
	v_pk_mul_f32 v[170:171], v[170:171], v[166:167]
	v_mul_f32_e32 v96, v96, v246
	v_mul_f32_e32 v97, v97, v168
	v_mul_f32_e32 v98, v98, v247
	v_mul_f32_e32 v99, v99, v169
	v_mul_f32_e32 v92, v92, v250
	v_mul_f32_e32 v93, v93, v170
	v_mul_f32_e32 v94, v94, v251
	v_mul_f32_e32 v95, v95, v171
	v_add_u32_e32 v213, 160, v1
	v_mad_i64_i32 v[218:219], s[2:3], v213, s20, v[2:3]
	global_load_dwordx4 v[164:167], v[218:219], off offset:-2048
	global_load_dwordx4 v[168:171], v[218:219], off offset:2048
	s_waitcnt vmcnt(14)
	v_lshlrev_b32_e32 v244, 16, v172
	v_lshlrev_b32_e32 v245, 16, v173
	v_and_b32_e32 v172, 0xffff0000, v172
	v_and_b32_e32 v173, 0xffff0000, v173
	v_lshlrev_b32_e32 v246, 16, v176
	v_lshlrev_b32_e32 v247, 16, v177
	v_and_b32_e32 v176, 0xffff0000, v176
	v_and_b32_e32 v177, 0xffff0000, v177
	v_lshlrev_b32_e32 v248, 16, v174
	v_lshlrev_b32_e32 v249, 16, v175
	v_and_b32_e32 v174, 0xffff0000, v174
	v_and_b32_e32 v175, 0xffff0000, v175
	v_lshlrev_b32_e32 v250, 16, v178
	v_lshlrev_b32_e32 v251, 16, v179
	v_and_b32_e32 v178, 0xffff0000, v178
	v_and_b32_e32 v179, 0xffff0000, v179
	v_mul_f32_e32 v244, 0xbfb8aa3b, v244
	v_mul_f32_e32 v245, 0xbfb8aa3b, v245
	v_mul_f32_e32 v172, 0xbfb8aa3b, v172
	v_mul_f32_e32 v173, 0xbfb8aa3b, v173
	v_mul_f32_e32 v246, 0xbfb8aa3b, v246
	v_mul_f32_e32 v247, 0xbfb8aa3b, v247
	v_mul_f32_e32 v176, 0xbfb8aa3b, v176
	v_mul_f32_e32 v177, 0xbfb8aa3b, v177
	v_mul_f32_e32 v248, 0xbfb8aa3b, v248
	v_mul_f32_e32 v249, 0xbfb8aa3b, v249
	v_mul_f32_e32 v174, 0xbfb8aa3b, v174
	v_mul_f32_e32 v175, 0xbfb8aa3b, v175
	v_mul_f32_e32 v250, 0xbfb8aa3b, v250
	v_mul_f32_e32 v251, 0xbfb8aa3b, v251
	v_mul_f32_e32 v178, 0xbfb8aa3b, v178
	v_mul_f32_e32 v179, 0xbfb8aa3b, v179
	v_exp_f32_e32 v244, v244
	v_exp_f32_e32 v245, v245
	v_exp_f32_e32 v172, v172
	v_exp_f32_e32 v173, v173
	v_exp_f32_e32 v246, v246
	v_exp_f32_e32 v247, v247
	v_exp_f32_e32 v176, v176
	v_exp_f32_e32 v177, v177
	v_exp_f32_e32 v248, v248
	v_exp_f32_e32 v249, v249
	v_exp_f32_e32 v174, v174
	v_exp_f32_e32 v175, v175
	v_exp_f32_e32 v250, v250
	v_exp_f32_e32 v251, v251
	v_exp_f32_e32 v178, v178
	v_exp_f32_e32 v179, v179
	v_pk_add_f32 v[244:245], v[244:245], 1.0 op_sel_hi:[1,0]
	v_pk_add_f32 v[172:173], v[172:173], 1.0 op_sel_hi:[1,0]
	v_pk_add_f32 v[246:247], v[246:247], 1.0 op_sel_hi:[1,0]
	v_pk_add_f32 v[176:177], v[176:177], 1.0 op_sel_hi:[1,0]
	v_pk_add_f32 v[248:249], v[248:249], 1.0 op_sel_hi:[1,0]
	v_pk_add_f32 v[174:175], v[174:175], 1.0 op_sel_hi:[1,0]
	v_pk_add_f32 v[250:251], v[250:251], 1.0 op_sel_hi:[1,0]
	v_pk_add_f32 v[178:179], v[178:179], 1.0 op_sel_hi:[1,0]
	v_rcp_f32_e32 v244, v244
	v_rcp_f32_e32 v245, v245
	v_rcp_f32_e32 v172, v172
	v_rcp_f32_e32 v173, v173
	v_rcp_f32_e32 v248, v248
	v_rcp_f32_e32 v249, v249
	v_rcp_f32_e32 v174, v174
	v_rcp_f32_e32 v175, v175
	v_pk_mul_f32 v[246:247], v[246:247], v[244:245]
	v_pk_mul_f32 v[176:177], v[176:177], v[172:173]
	v_pk_mul_f32 v[250:251], v[250:251], v[248:249]
	v_pk_mul_f32 v[178:179], v[178:179], v[174:175]
	v_mul_f32_e32 v88, v88, v246
	v_mul_f32_e32 v89, v89, v176
	v_mul_f32_e32 v90, v90, v247
	v_mul_f32_e32 v91, v91, v177
	v_mul_f32_e32 v84, v84, v250
	v_mul_f32_e32 v85, v85, v178
	v_mul_f32_e32 v86, v86, v251
	v_mul_f32_e32 v87, v87, v179
	global_load_dwordx4 v[172:175], v[218:219], off offset:-1792
	global_load_dwordx4 v[176:179], v[218:219], off offset:2304
	s_waitcnt vmcnt(14)
	v_lshlrev_b32_e32 v244, 16, v180
	v_lshlrev_b32_e32 v245, 16, v181
	v_and_b32_e32 v180, 0xffff0000, v180
	v_and_b32_e32 v181, 0xffff0000, v181
	v_lshlrev_b32_e32 v246, 16, v184
	v_lshlrev_b32_e32 v247, 16, v185
	v_and_b32_e32 v184, 0xffff0000, v184
	v_and_b32_e32 v185, 0xffff0000, v185
	v_lshlrev_b32_e32 v248, 16, v182
	v_lshlrev_b32_e32 v249, 16, v183
	v_and_b32_e32 v182, 0xffff0000, v182
	v_and_b32_e32 v183, 0xffff0000, v183
	v_lshlrev_b32_e32 v250, 16, v186
	v_lshlrev_b32_e32 v251, 16, v187
	v_and_b32_e32 v186, 0xffff0000, v186
	v_and_b32_e32 v187, 0xffff0000, v187
	v_mul_f32_e32 v244, 0xbfb8aa3b, v244
	v_mul_f32_e32 v245, 0xbfb8aa3b, v245
	v_mul_f32_e32 v180, 0xbfb8aa3b, v180
	v_mul_f32_e32 v181, 0xbfb8aa3b, v181
	v_mul_f32_e32 v246, 0xbfb8aa3b, v246
	v_mul_f32_e32 v247, 0xbfb8aa3b, v247
	v_mul_f32_e32 v184, 0xbfb8aa3b, v184
	v_mul_f32_e32 v185, 0xbfb8aa3b, v185
	v_mul_f32_e32 v248, 0xbfb8aa3b, v248
	v_mul_f32_e32 v249, 0xbfb8aa3b, v249
	v_mul_f32_e32 v182, 0xbfb8aa3b, v182
	v_mul_f32_e32 v183, 0xbfb8aa3b, v183
	v_mul_f32_e32 v250, 0xbfb8aa3b, v250
	v_mul_f32_e32 v251, 0xbfb8aa3b, v251
	v_mul_f32_e32 v186, 0xbfb8aa3b, v186
	v_mul_f32_e32 v187, 0xbfb8aa3b, v187
	v_exp_f32_e32 v244, v244
	v_exp_f32_e32 v245, v245
	v_exp_f32_e32 v180, v180
	v_exp_f32_e32 v181, v181
	v_exp_f32_e32 v246, v246
	v_exp_f32_e32 v247, v247
	v_exp_f32_e32 v184, v184
	v_exp_f32_e32 v185, v185
	v_exp_f32_e32 v248, v248
	v_exp_f32_e32 v249, v249
	v_exp_f32_e32 v182, v182
	v_exp_f32_e32 v183, v183
	v_exp_f32_e32 v250, v250
	v_exp_f32_e32 v251, v251
	v_exp_f32_e32 v186, v186
	v_exp_f32_e32 v187, v187
	v_pk_add_f32 v[244:245], v[244:245], 1.0 op_sel_hi:[1,0]
	v_pk_add_f32 v[180:181], v[180:181], 1.0 op_sel_hi:[1,0]
	v_pk_add_f32 v[246:247], v[246:247], 1.0 op_sel_hi:[1,0]
	v_pk_add_f32 v[184:185], v[184:185], 1.0 op_sel_hi:[1,0]
	v_pk_add_f32 v[248:249], v[248:249], 1.0 op_sel_hi:[1,0]
	v_pk_add_f32 v[182:183], v[182:183], 1.0 op_sel_hi:[1,0]
	v_pk_add_f32 v[250:251], v[250:251], 1.0 op_sel_hi:[1,0]
	v_pk_add_f32 v[186:187], v[186:187], 1.0 op_sel_hi:[1,0]
	v_rcp_f32_e32 v244, v244
	v_rcp_f32_e32 v245, v245
	v_rcp_f32_e32 v180, v180
	v_rcp_f32_e32 v181, v181
	v_rcp_f32_e32 v248, v248
	v_rcp_f32_e32 v249, v249
	v_rcp_f32_e32 v182, v182
	v_rcp_f32_e32 v183, v183
	v_pk_mul_f32 v[246:247], v[246:247], v[244:245]
	v_pk_mul_f32 v[184:185], v[184:185], v[180:181]
	v_pk_mul_f32 v[250:251], v[250:251], v[248:249]
	v_pk_mul_f32 v[186:187], v[186:187], v[182:183]
	v_mul_f32_e32 v80, v80, v246
	v_mul_f32_e32 v81, v81, v184
	v_mul_f32_e32 v82, v82, v247
	v_mul_f32_e32 v83, v83, v185
	v_mul_f32_e32 v76, v76, v250
	v_mul_f32_e32 v77, v77, v186
	v_mul_f32_e32 v78, v78, v251
	v_mul_f32_e32 v79, v79, v187
	v_add_u32_e32 v213, 176, v1
	v_mad_i64_i32 v[218:219], s[2:3], v213, s20, v[2:3]
	global_load_dwordx4 v[180:183], v[218:219], off offset:-2048
	global_load_dwordx4 v[184:187], v[218:219], off offset:2048
	s_waitcnt vmcnt(14)
	v_lshlrev_b32_e32 v244, 16, v188
	v_lshlrev_b32_e32 v245, 16, v189
	v_and_b32_e32 v188, 0xffff0000, v188
	v_and_b32_e32 v189, 0xffff0000, v189
	v_lshlrev_b32_e32 v246, 16, v192
	v_lshlrev_b32_e32 v247, 16, v193
	v_and_b32_e32 v192, 0xffff0000, v192
	v_and_b32_e32 v193, 0xffff0000, v193
	v_lshlrev_b32_e32 v248, 16, v190
	v_lshlrev_b32_e32 v249, 16, v191
	v_and_b32_e32 v190, 0xffff0000, v190
	v_and_b32_e32 v191, 0xffff0000, v191
	v_lshlrev_b32_e32 v250, 16, v194
	v_lshlrev_b32_e32 v251, 16, v195
	v_and_b32_e32 v194, 0xffff0000, v194
	v_and_b32_e32 v195, 0xffff0000, v195
	v_mul_f32_e32 v244, 0xbfb8aa3b, v244
	v_mul_f32_e32 v245, 0xbfb8aa3b, v245
	v_mul_f32_e32 v188, 0xbfb8aa3b, v188
	v_mul_f32_e32 v189, 0xbfb8aa3b, v189
	v_mul_f32_e32 v246, 0xbfb8aa3b, v246
	v_mul_f32_e32 v247, 0xbfb8aa3b, v247
	v_mul_f32_e32 v192, 0xbfb8aa3b, v192
	v_mul_f32_e32 v193, 0xbfb8aa3b, v193
	v_mul_f32_e32 v248, 0xbfb8aa3b, v248
	v_mul_f32_e32 v249, 0xbfb8aa3b, v249
	v_mul_f32_e32 v190, 0xbfb8aa3b, v190
	v_mul_f32_e32 v191, 0xbfb8aa3b, v191
	v_mul_f32_e32 v250, 0xbfb8aa3b, v250
	v_mul_f32_e32 v251, 0xbfb8aa3b, v251
	v_mul_f32_e32 v194, 0xbfb8aa3b, v194
	v_mul_f32_e32 v195, 0xbfb8aa3b, v195
	v_exp_f32_e32 v244, v244
	v_exp_f32_e32 v245, v245
	v_exp_f32_e32 v188, v188
	v_exp_f32_e32 v189, v189
	v_exp_f32_e32 v246, v246
	v_exp_f32_e32 v247, v247
	v_exp_f32_e32 v192, v192
	v_exp_f32_e32 v193, v193
	v_exp_f32_e32 v248, v248
	v_exp_f32_e32 v249, v249
	v_exp_f32_e32 v190, v190
	v_exp_f32_e32 v191, v191
	v_exp_f32_e32 v250, v250
	v_exp_f32_e32 v251, v251
	v_exp_f32_e32 v194, v194
	v_exp_f32_e32 v195, v195
	v_pk_add_f32 v[244:245], v[244:245], 1.0 op_sel_hi:[1,0]
	v_pk_add_f32 v[188:189], v[188:189], 1.0 op_sel_hi:[1,0]
	v_pk_add_f32 v[246:247], v[246:247], 1.0 op_sel_hi:[1,0]
	v_pk_add_f32 v[192:193], v[192:193], 1.0 op_sel_hi:[1,0]
	v_pk_add_f32 v[248:249], v[248:249], 1.0 op_sel_hi:[1,0]
	v_pk_add_f32 v[190:191], v[190:191], 1.0 op_sel_hi:[1,0]
	v_pk_add_f32 v[250:251], v[250:251], 1.0 op_sel_hi:[1,0]
	v_pk_add_f32 v[194:195], v[194:195], 1.0 op_sel_hi:[1,0]
	v_rcp_f32_e32 v244, v244
	v_rcp_f32_e32 v245, v245
	v_rcp_f32_e32 v188, v188
	v_rcp_f32_e32 v189, v189
	v_rcp_f32_e32 v248, v248
	v_rcp_f32_e32 v249, v249
	v_rcp_f32_e32 v190, v190
	v_rcp_f32_e32 v191, v191
	v_pk_mul_f32 v[246:247], v[246:247], v[244:245]
	v_pk_mul_f32 v[192:193], v[192:193], v[188:189]
	v_pk_mul_f32 v[250:251], v[250:251], v[248:249]
	v_pk_mul_f32 v[194:195], v[194:195], v[190:191]
	v_mul_f32_e32 v72, v72, v246
	v_mul_f32_e32 v73, v73, v192
	v_mul_f32_e32 v74, v74, v247
	v_mul_f32_e32 v75, v75, v193
	v_mul_f32_e32 v68, v68, v250
	v_mul_f32_e32 v69, v69, v194
	v_mul_f32_e32 v70, v70, v251
	v_mul_f32_e32 v71, v71, v195
	global_load_dwordx4 v[188:191], v[218:219], off offset:-1792
	global_load_dwordx4 v[192:195], v[218:219], off offset:2304
	s_waitcnt vmcnt(14)
	v_lshlrev_b32_e32 v244, 16, v132
	v_lshlrev_b32_e32 v245, 16, v133
	v_and_b32_e32 v132, 0xffff0000, v132
	v_and_b32_e32 v133, 0xffff0000, v133
	v_lshlrev_b32_e32 v246, 16, v136
	v_lshlrev_b32_e32 v247, 16, v137
	v_and_b32_e32 v136, 0xffff0000, v136
	v_and_b32_e32 v137, 0xffff0000, v137
	v_lshlrev_b32_e32 v248, 16, v134
	v_lshlrev_b32_e32 v249, 16, v135
	v_and_b32_e32 v134, 0xffff0000, v134
	v_and_b32_e32 v135, 0xffff0000, v135
	v_lshlrev_b32_e32 v250, 16, v138
	v_lshlrev_b32_e32 v251, 16, v139
	v_and_b32_e32 v138, 0xffff0000, v138
	v_and_b32_e32 v139, 0xffff0000, v139
	v_mul_f32_e32 v244, 0xbfb8aa3b, v244
	v_mul_f32_e32 v245, 0xbfb8aa3b, v245
	v_mul_f32_e32 v132, 0xbfb8aa3b, v132
	v_mul_f32_e32 v133, 0xbfb8aa3b, v133
	v_mul_f32_e32 v246, 0xbfb8aa3b, v246
	v_mul_f32_e32 v247, 0xbfb8aa3b, v247
	v_mul_f32_e32 v136, 0xbfb8aa3b, v136
	v_mul_f32_e32 v137, 0xbfb8aa3b, v137
	v_mul_f32_e32 v248, 0xbfb8aa3b, v248
	v_mul_f32_e32 v249, 0xbfb8aa3b, v249
	v_mul_f32_e32 v134, 0xbfb8aa3b, v134
	v_mul_f32_e32 v135, 0xbfb8aa3b, v135
	v_mul_f32_e32 v250, 0xbfb8aa3b, v250
	v_mul_f32_e32 v251, 0xbfb8aa3b, v251
	v_mul_f32_e32 v138, 0xbfb8aa3b, v138
	v_mul_f32_e32 v139, 0xbfb8aa3b, v139
	v_exp_f32_e32 v244, v244
	v_exp_f32_e32 v245, v245
	v_exp_f32_e32 v132, v132
	v_exp_f32_e32 v133, v133
	v_exp_f32_e32 v246, v246
	v_exp_f32_e32 v247, v247
	v_exp_f32_e32 v136, v136
	v_exp_f32_e32 v137, v137
	v_exp_f32_e32 v248, v248
	v_exp_f32_e32 v249, v249
	v_exp_f32_e32 v134, v134
	v_exp_f32_e32 v135, v135
	v_exp_f32_e32 v250, v250
	v_exp_f32_e32 v251, v251
	v_exp_f32_e32 v138, v138
	v_exp_f32_e32 v139, v139
	v_pk_add_f32 v[244:245], v[244:245], 1.0 op_sel_hi:[1,0]
	v_pk_add_f32 v[132:133], v[132:133], 1.0 op_sel_hi:[1,0]
	v_pk_add_f32 v[246:247], v[246:247], 1.0 op_sel_hi:[1,0]
	v_pk_add_f32 v[136:137], v[136:137], 1.0 op_sel_hi:[1,0]
	v_pk_add_f32 v[248:249], v[248:249], 1.0 op_sel_hi:[1,0]
	v_pk_add_f32 v[134:135], v[134:135], 1.0 op_sel_hi:[1,0]
	v_pk_add_f32 v[250:251], v[250:251], 1.0 op_sel_hi:[1,0]
	v_pk_add_f32 v[138:139], v[138:139], 1.0 op_sel_hi:[1,0]
	v_rcp_f32_e32 v244, v244
	v_rcp_f32_e32 v245, v245
	v_rcp_f32_e32 v132, v132
	v_rcp_f32_e32 v133, v133
	v_rcp_f32_e32 v248, v248
	v_rcp_f32_e32 v249, v249
	v_rcp_f32_e32 v134, v134
	v_rcp_f32_e32 v135, v135
	v_pk_mul_f32 v[246:247], v[246:247], v[244:245]
	v_pk_mul_f32 v[136:137], v[136:137], v[132:133]
	v_pk_mul_f32 v[250:251], v[250:251], v[248:249]
	v_pk_mul_f32 v[138:139], v[138:139], v[134:135]
	v_mul_f32_e32 v64, v64, v246
	v_mul_f32_e32 v65, v65, v136
	v_mul_f32_e32 v66, v66, v247
	v_mul_f32_e32 v67, v67, v137
	v_mul_f32_e32 v60, v60, v250
	v_mul_f32_e32 v61, v61, v138
	v_mul_f32_e32 v62, v62, v251
	v_mul_f32_e32 v63, v63, v139
	s_waitcnt vmcnt(12)
	v_lshlrev_b32_e32 v244, 16, v140
	v_lshlrev_b32_e32 v245, 16, v141
	v_and_b32_e32 v140, 0xffff0000, v140
	v_and_b32_e32 v141, 0xffff0000, v141
	v_lshlrev_b32_e32 v246, 16, v144
	v_lshlrev_b32_e32 v247, 16, v145
	v_and_b32_e32 v144, 0xffff0000, v144
	v_and_b32_e32 v145, 0xffff0000, v145
	v_lshlrev_b32_e32 v248, 16, v142
	v_lshlrev_b32_e32 v249, 16, v143
	v_and_b32_e32 v142, 0xffff0000, v142
	v_and_b32_e32 v143, 0xffff0000, v143
	v_lshlrev_b32_e32 v250, 16, v146
	v_lshlrev_b32_e32 v251, 16, v147
	v_and_b32_e32 v146, 0xffff0000, v146
	v_and_b32_e32 v147, 0xffff0000, v147
	v_mul_f32_e32 v244, 0xbfb8aa3b, v244
	v_mul_f32_e32 v245, 0xbfb8aa3b, v245
	v_mul_f32_e32 v140, 0xbfb8aa3b, v140
	v_mul_f32_e32 v141, 0xbfb8aa3b, v141
	v_mul_f32_e32 v246, 0xbfb8aa3b, v246
	v_mul_f32_e32 v247, 0xbfb8aa3b, v247
	v_mul_f32_e32 v144, 0xbfb8aa3b, v144
	v_mul_f32_e32 v145, 0xbfb8aa3b, v145
	v_mul_f32_e32 v248, 0xbfb8aa3b, v248
	v_mul_f32_e32 v249, 0xbfb8aa3b, v249
	v_mul_f32_e32 v142, 0xbfb8aa3b, v142
	v_mul_f32_e32 v143, 0xbfb8aa3b, v143
	v_mul_f32_e32 v250, 0xbfb8aa3b, v250
	v_mul_f32_e32 v251, 0xbfb8aa3b, v251
	v_mul_f32_e32 v146, 0xbfb8aa3b, v146
	v_mul_f32_e32 v147, 0xbfb8aa3b, v147
	v_exp_f32_e32 v244, v244
	v_exp_f32_e32 v245, v245
	v_exp_f32_e32 v140, v140
	v_exp_f32_e32 v141, v141
	v_exp_f32_e32 v246, v246
	v_exp_f32_e32 v247, v247
	v_exp_f32_e32 v144, v144
	v_exp_f32_e32 v145, v145
	v_exp_f32_e32 v248, v248
	v_exp_f32_e32 v249, v249
	v_exp_f32_e32 v142, v142
	v_exp_f32_e32 v143, v143
	v_exp_f32_e32 v250, v250
	v_exp_f32_e32 v251, v251
	v_exp_f32_e32 v146, v146
	v_exp_f32_e32 v147, v147
	v_pk_add_f32 v[244:245], v[244:245], 1.0 op_sel_hi:[1,0]
	v_pk_add_f32 v[140:141], v[140:141], 1.0 op_sel_hi:[1,0]
	v_pk_add_f32 v[246:247], v[246:247], 1.0 op_sel_hi:[1,0]
	v_pk_add_f32 v[144:145], v[144:145], 1.0 op_sel_hi:[1,0]
	v_pk_add_f32 v[248:249], v[248:249], 1.0 op_sel_hi:[1,0]
	v_pk_add_f32 v[142:143], v[142:143], 1.0 op_sel_hi:[1,0]
	v_pk_add_f32 v[250:251], v[250:251], 1.0 op_sel_hi:[1,0]
	v_pk_add_f32 v[146:147], v[146:147], 1.0 op_sel_hi:[1,0]
	v_rcp_f32_e32 v244, v244
	v_rcp_f32_e32 v245, v245
	v_rcp_f32_e32 v140, v140
	v_rcp_f32_e32 v141, v141
	v_rcp_f32_e32 v248, v248
	v_rcp_f32_e32 v249, v249
	v_rcp_f32_e32 v142, v142
	v_rcp_f32_e32 v143, v143
	v_pk_mul_f32 v[246:247], v[246:247], v[244:245]
	v_pk_mul_f32 v[144:145], v[144:145], v[140:141]
	v_pk_mul_f32 v[250:251], v[250:251], v[248:249]
	v_pk_mul_f32 v[146:147], v[146:147], v[142:143]
	v_mul_f32_e32 v56, v56, v246
	v_mul_f32_e32 v57, v57, v144
	v_mul_f32_e32 v58, v58, v247
	v_mul_f32_e32 v59, v59, v145
	v_mul_f32_e32 v52, v52, v250
	v_mul_f32_e32 v53, v53, v146
	v_mul_f32_e32 v54, v54, v251
	v_mul_f32_e32 v55, v55, v147
	s_waitcnt vmcnt(10)
	v_lshlrev_b32_e32 v244, 16, v148
	v_lshlrev_b32_e32 v245, 16, v149
	v_and_b32_e32 v148, 0xffff0000, v148
	v_and_b32_e32 v149, 0xffff0000, v149
	v_lshlrev_b32_e32 v246, 16, v152
	v_lshlrev_b32_e32 v247, 16, v153
	v_and_b32_e32 v152, 0xffff0000, v152
	v_and_b32_e32 v153, 0xffff0000, v153
	v_lshlrev_b32_e32 v248, 16, v150
	v_lshlrev_b32_e32 v249, 16, v151
	v_and_b32_e32 v150, 0xffff0000, v150
	v_and_b32_e32 v151, 0xffff0000, v151
	v_lshlrev_b32_e32 v250, 16, v154
	v_lshlrev_b32_e32 v251, 16, v155
	v_and_b32_e32 v154, 0xffff0000, v154
	v_and_b32_e32 v155, 0xffff0000, v155
	v_mul_f32_e32 v244, 0xbfb8aa3b, v244
	v_mul_f32_e32 v245, 0xbfb8aa3b, v245
	v_mul_f32_e32 v148, 0xbfb8aa3b, v148
	v_mul_f32_e32 v149, 0xbfb8aa3b, v149
	v_mul_f32_e32 v246, 0xbfb8aa3b, v246
	v_mul_f32_e32 v247, 0xbfb8aa3b, v247
	v_mul_f32_e32 v152, 0xbfb8aa3b, v152
	v_mul_f32_e32 v153, 0xbfb8aa3b, v153
	v_mul_f32_e32 v248, 0xbfb8aa3b, v248
	v_mul_f32_e32 v249, 0xbfb8aa3b, v249
	v_mul_f32_e32 v150, 0xbfb8aa3b, v150
	v_mul_f32_e32 v151, 0xbfb8aa3b, v151
	v_mul_f32_e32 v250, 0xbfb8aa3b, v250
	v_mul_f32_e32 v251, 0xbfb8aa3b, v251
	v_mul_f32_e32 v154, 0xbfb8aa3b, v154
	v_mul_f32_e32 v155, 0xbfb8aa3b, v155
	v_exp_f32_e32 v244, v244
	v_exp_f32_e32 v245, v245
	v_exp_f32_e32 v148, v148
	v_exp_f32_e32 v149, v149
	v_exp_f32_e32 v246, v246
	v_exp_f32_e32 v247, v247
	v_exp_f32_e32 v152, v152
	v_exp_f32_e32 v153, v153
	v_exp_f32_e32 v248, v248
	v_exp_f32_e32 v249, v249
	v_exp_f32_e32 v150, v150
	v_exp_f32_e32 v151, v151
	v_exp_f32_e32 v250, v250
	v_exp_f32_e32 v251, v251
	v_exp_f32_e32 v154, v154
	v_exp_f32_e32 v155, v155
	v_pk_add_f32 v[244:245], v[244:245], 1.0 op_sel_hi:[1,0]
	v_pk_add_f32 v[148:149], v[148:149], 1.0 op_sel_hi:[1,0]
	v_pk_add_f32 v[246:247], v[246:247], 1.0 op_sel_hi:[1,0]
	v_pk_add_f32 v[152:153], v[152:153], 1.0 op_sel_hi:[1,0]
	v_pk_add_f32 v[248:249], v[248:249], 1.0 op_sel_hi:[1,0]
	v_pk_add_f32 v[150:151], v[150:151], 1.0 op_sel_hi:[1,0]
	v_pk_add_f32 v[250:251], v[250:251], 1.0 op_sel_hi:[1,0]
	v_pk_add_f32 v[154:155], v[154:155], 1.0 op_sel_hi:[1,0]
	v_rcp_f32_e32 v244, v244
	v_rcp_f32_e32 v245, v245
	v_rcp_f32_e32 v148, v148
	v_rcp_f32_e32 v149, v149
	v_rcp_f32_e32 v248, v248
	v_rcp_f32_e32 v249, v249
	v_rcp_f32_e32 v150, v150
	v_rcp_f32_e32 v151, v151
	v_pk_mul_f32 v[246:247], v[246:247], v[244:245]
	v_pk_mul_f32 v[152:153], v[152:153], v[148:149]
	v_pk_mul_f32 v[250:251], v[250:251], v[248:249]
	v_pk_mul_f32 v[154:155], v[154:155], v[150:151]
	v_mul_f32_e32 v48, v48, v246
	v_mul_f32_e32 v49, v49, v152
	v_mul_f32_e32 v50, v50, v247
	v_mul_f32_e32 v51, v51, v153
	v_mul_f32_e32 v44, v44, v250
	v_mul_f32_e32 v45, v45, v154
	v_mul_f32_e32 v46, v46, v251
	v_mul_f32_e32 v47, v47, v155
	s_waitcnt vmcnt(8)
	v_lshlrev_b32_e32 v244, 16, v156
	v_lshlrev_b32_e32 v245, 16, v157
	v_and_b32_e32 v156, 0xffff0000, v156
	v_and_b32_e32 v157, 0xffff0000, v157
	v_lshlrev_b32_e32 v246, 16, v160
	v_lshlrev_b32_e32 v247, 16, v161
	v_and_b32_e32 v160, 0xffff0000, v160
	v_and_b32_e32 v161, 0xffff0000, v161
	v_lshlrev_b32_e32 v248, 16, v158
	v_lshlrev_b32_e32 v249, 16, v159
	v_and_b32_e32 v158, 0xffff0000, v158
	v_and_b32_e32 v159, 0xffff0000, v159
	v_lshlrev_b32_e32 v250, 16, v162
	v_lshlrev_b32_e32 v251, 16, v163
	v_and_b32_e32 v162, 0xffff0000, v162
	v_and_b32_e32 v163, 0xffff0000, v163
	v_mul_f32_e32 v244, 0xbfb8aa3b, v244
	v_mul_f32_e32 v245, 0xbfb8aa3b, v245
	v_mul_f32_e32 v156, 0xbfb8aa3b, v156
	v_mul_f32_e32 v157, 0xbfb8aa3b, v157
	v_mul_f32_e32 v246, 0xbfb8aa3b, v246
	v_mul_f32_e32 v247, 0xbfb8aa3b, v247
	v_mul_f32_e32 v160, 0xbfb8aa3b, v160
	v_mul_f32_e32 v161, 0xbfb8aa3b, v161
	v_mul_f32_e32 v248, 0xbfb8aa3b, v248
	v_mul_f32_e32 v249, 0xbfb8aa3b, v249
	v_mul_f32_e32 v158, 0xbfb8aa3b, v158
	v_mul_f32_e32 v159, 0xbfb8aa3b, v159
	v_mul_f32_e32 v250, 0xbfb8aa3b, v250
	v_mul_f32_e32 v251, 0xbfb8aa3b, v251
	v_mul_f32_e32 v162, 0xbfb8aa3b, v162
	v_mul_f32_e32 v163, 0xbfb8aa3b, v163
	v_exp_f32_e32 v244, v244
	v_exp_f32_e32 v245, v245
	v_exp_f32_e32 v156, v156
	v_exp_f32_e32 v157, v157
	v_exp_f32_e32 v246, v246
	v_exp_f32_e32 v247, v247
	v_exp_f32_e32 v160, v160
	v_exp_f32_e32 v161, v161
	v_exp_f32_e32 v248, v248
	v_exp_f32_e32 v249, v249
	v_exp_f32_e32 v158, v158
	v_exp_f32_e32 v159, v159
	v_exp_f32_e32 v250, v250
	v_exp_f32_e32 v251, v251
	v_exp_f32_e32 v162, v162
	v_exp_f32_e32 v163, v163
	v_pk_add_f32 v[244:245], v[244:245], 1.0 op_sel_hi:[1,0]
	v_pk_add_f32 v[156:157], v[156:157], 1.0 op_sel_hi:[1,0]
	v_pk_add_f32 v[246:247], v[246:247], 1.0 op_sel_hi:[1,0]
	v_pk_add_f32 v[160:161], v[160:161], 1.0 op_sel_hi:[1,0]
	v_pk_add_f32 v[248:249], v[248:249], 1.0 op_sel_hi:[1,0]
	v_pk_add_f32 v[158:159], v[158:159], 1.0 op_sel_hi:[1,0]
	v_pk_add_f32 v[250:251], v[250:251], 1.0 op_sel_hi:[1,0]
	v_pk_add_f32 v[162:163], v[162:163], 1.0 op_sel_hi:[1,0]
	v_rcp_f32_e32 v244, v244
	v_rcp_f32_e32 v245, v245
	v_rcp_f32_e32 v156, v156
	v_rcp_f32_e32 v157, v157
	v_rcp_f32_e32 v248, v248
	v_rcp_f32_e32 v249, v249
	v_rcp_f32_e32 v158, v158
	v_rcp_f32_e32 v159, v159
	v_pk_mul_f32 v[246:247], v[246:247], v[244:245]
	v_pk_mul_f32 v[160:161], v[160:161], v[156:157]
	v_pk_mul_f32 v[250:251], v[250:251], v[248:249]
	v_pk_mul_f32 v[162:163], v[162:163], v[158:159]
	v_mul_f32_e32 v40, v40, v246
	v_mul_f32_e32 v41, v41, v160
	v_mul_f32_e32 v42, v42, v247
	v_mul_f32_e32 v43, v43, v161
	v_mul_f32_e32 v36, v36, v250
	v_mul_f32_e32 v37, v37, v162
	v_mul_f32_e32 v38, v38, v251
	v_mul_f32_e32 v39, v39, v163
	s_waitcnt vmcnt(6)
	v_lshlrev_b32_e32 v244, 16, v164
	v_lshlrev_b32_e32 v245, 16, v165
	v_and_b32_e32 v164, 0xffff0000, v164
	v_and_b32_e32 v165, 0xffff0000, v165
	v_lshlrev_b32_e32 v246, 16, v168
	v_lshlrev_b32_e32 v247, 16, v169
	v_and_b32_e32 v168, 0xffff0000, v168
	v_and_b32_e32 v169, 0xffff0000, v169
	v_lshlrev_b32_e32 v248, 16, v166
	v_lshlrev_b32_e32 v249, 16, v167
	v_and_b32_e32 v166, 0xffff0000, v166
	v_and_b32_e32 v167, 0xffff0000, v167
	v_lshlrev_b32_e32 v250, 16, v170
	v_lshlrev_b32_e32 v251, 16, v171
	v_and_b32_e32 v170, 0xffff0000, v170
	v_and_b32_e32 v171, 0xffff0000, v171
	v_mul_f32_e32 v244, 0xbfb8aa3b, v244
	v_mul_f32_e32 v245, 0xbfb8aa3b, v245
	v_mul_f32_e32 v164, 0xbfb8aa3b, v164
	v_mul_f32_e32 v165, 0xbfb8aa3b, v165
	v_mul_f32_e32 v246, 0xbfb8aa3b, v246
	v_mul_f32_e32 v247, 0xbfb8aa3b, v247
	v_mul_f32_e32 v168, 0xbfb8aa3b, v168
	v_mul_f32_e32 v169, 0xbfb8aa3b, v169
	v_mul_f32_e32 v248, 0xbfb8aa3b, v248
	v_mul_f32_e32 v249, 0xbfb8aa3b, v249
	v_mul_f32_e32 v166, 0xbfb8aa3b, v166
	v_mul_f32_e32 v167, 0xbfb8aa3b, v167
	v_mul_f32_e32 v250, 0xbfb8aa3b, v250
	v_mul_f32_e32 v251, 0xbfb8aa3b, v251
	v_mul_f32_e32 v170, 0xbfb8aa3b, v170
	v_mul_f32_e32 v171, 0xbfb8aa3b, v171
	v_exp_f32_e32 v244, v244
	v_exp_f32_e32 v245, v245
	v_exp_f32_e32 v164, v164
	v_exp_f32_e32 v165, v165
	v_exp_f32_e32 v246, v246
	v_exp_f32_e32 v247, v247
	v_exp_f32_e32 v168, v168
	v_exp_f32_e32 v169, v169
	v_exp_f32_e32 v248, v248
	v_exp_f32_e32 v249, v249
	v_exp_f32_e32 v166, v166
	v_exp_f32_e32 v167, v167
	v_exp_f32_e32 v250, v250
	v_exp_f32_e32 v251, v251
	v_exp_f32_e32 v170, v170
	v_exp_f32_e32 v171, v171
	v_pk_add_f32 v[244:245], v[244:245], 1.0 op_sel_hi:[1,0]
	v_pk_add_f32 v[164:165], v[164:165], 1.0 op_sel_hi:[1,0]
	v_pk_add_f32 v[246:247], v[246:247], 1.0 op_sel_hi:[1,0]
	v_pk_add_f32 v[168:169], v[168:169], 1.0 op_sel_hi:[1,0]
	v_pk_add_f32 v[248:249], v[248:249], 1.0 op_sel_hi:[1,0]
	v_pk_add_f32 v[166:167], v[166:167], 1.0 op_sel_hi:[1,0]
	v_pk_add_f32 v[250:251], v[250:251], 1.0 op_sel_hi:[1,0]
	v_pk_add_f32 v[170:171], v[170:171], 1.0 op_sel_hi:[1,0]
	v_rcp_f32_e32 v244, v244
	v_rcp_f32_e32 v245, v245
	v_rcp_f32_e32 v164, v164
	v_rcp_f32_e32 v165, v165
	v_rcp_f32_e32 v248, v248
	v_rcp_f32_e32 v249, v249
	v_rcp_f32_e32 v166, v166
	v_rcp_f32_e32 v167, v167
	v_pk_mul_f32 v[246:247], v[246:247], v[244:245]
	v_pk_mul_f32 v[168:169], v[168:169], v[164:165]
	v_pk_mul_f32 v[250:251], v[250:251], v[248:249]
	v_pk_mul_f32 v[170:171], v[170:171], v[166:167]
	v_mul_f32_e32 v32, v32, v246
	v_mul_f32_e32 v33, v33, v168
	v_mul_f32_e32 v34, v34, v247
	v_mul_f32_e32 v35, v35, v169
	v_mul_f32_e32 v28, v28, v250
	v_mul_f32_e32 v29, v29, v170
	v_mul_f32_e32 v30, v30, v251
	v_mul_f32_e32 v31, v31, v171
	s_waitcnt vmcnt(4)
	v_lshlrev_b32_e32 v244, 16, v172
	v_lshlrev_b32_e32 v245, 16, v173
	v_and_b32_e32 v172, 0xffff0000, v172
	v_and_b32_e32 v173, 0xffff0000, v173
	v_lshlrev_b32_e32 v246, 16, v176
	v_lshlrev_b32_e32 v247, 16, v177
	v_and_b32_e32 v176, 0xffff0000, v176
	v_and_b32_e32 v177, 0xffff0000, v177
	v_lshlrev_b32_e32 v248, 16, v174
	v_lshlrev_b32_e32 v249, 16, v175
	v_and_b32_e32 v174, 0xffff0000, v174
	v_and_b32_e32 v175, 0xffff0000, v175
	v_lshlrev_b32_e32 v250, 16, v178
	v_lshlrev_b32_e32 v251, 16, v179
	v_and_b32_e32 v178, 0xffff0000, v178
	v_and_b32_e32 v179, 0xffff0000, v179
	v_mul_f32_e32 v244, 0xbfb8aa3b, v244
	v_mul_f32_e32 v245, 0xbfb8aa3b, v245
	v_mul_f32_e32 v172, 0xbfb8aa3b, v172
	v_mul_f32_e32 v173, 0xbfb8aa3b, v173
	v_mul_f32_e32 v246, 0xbfb8aa3b, v246
	v_mul_f32_e32 v247, 0xbfb8aa3b, v247
	v_mul_f32_e32 v176, 0xbfb8aa3b, v176
	v_mul_f32_e32 v177, 0xbfb8aa3b, v177
	v_mul_f32_e32 v248, 0xbfb8aa3b, v248
	v_mul_f32_e32 v249, 0xbfb8aa3b, v249
	v_mul_f32_e32 v174, 0xbfb8aa3b, v174
	v_mul_f32_e32 v175, 0xbfb8aa3b, v175
	v_mul_f32_e32 v250, 0xbfb8aa3b, v250
	v_mul_f32_e32 v251, 0xbfb8aa3b, v251
	v_mul_f32_e32 v178, 0xbfb8aa3b, v178
	v_mul_f32_e32 v179, 0xbfb8aa3b, v179
	v_exp_f32_e32 v244, v244
	v_exp_f32_e32 v245, v245
	v_exp_f32_e32 v172, v172
	v_exp_f32_e32 v173, v173
	v_exp_f32_e32 v246, v246
	v_exp_f32_e32 v247, v247
	v_exp_f32_e32 v176, v176
	v_exp_f32_e32 v177, v177
	v_exp_f32_e32 v248, v248
	v_exp_f32_e32 v249, v249
	v_exp_f32_e32 v174, v174
	v_exp_f32_e32 v175, v175
	v_exp_f32_e32 v250, v250
	v_exp_f32_e32 v251, v251
	v_exp_f32_e32 v178, v178
	v_exp_f32_e32 v179, v179
	v_pk_add_f32 v[244:245], v[244:245], 1.0 op_sel_hi:[1,0]
	v_pk_add_f32 v[172:173], v[172:173], 1.0 op_sel_hi:[1,0]
	v_pk_add_f32 v[246:247], v[246:247], 1.0 op_sel_hi:[1,0]
	v_pk_add_f32 v[176:177], v[176:177], 1.0 op_sel_hi:[1,0]
	v_pk_add_f32 v[248:249], v[248:249], 1.0 op_sel_hi:[1,0]
	v_pk_add_f32 v[174:175], v[174:175], 1.0 op_sel_hi:[1,0]
	v_pk_add_f32 v[250:251], v[250:251], 1.0 op_sel_hi:[1,0]
	v_pk_add_f32 v[178:179], v[178:179], 1.0 op_sel_hi:[1,0]
	v_rcp_f32_e32 v244, v244
	v_rcp_f32_e32 v245, v245
	v_rcp_f32_e32 v172, v172
	v_rcp_f32_e32 v173, v173
	v_rcp_f32_e32 v248, v248
	v_rcp_f32_e32 v249, v249
	v_rcp_f32_e32 v174, v174
	v_rcp_f32_e32 v175, v175
	v_pk_mul_f32 v[246:247], v[246:247], v[244:245]
	v_pk_mul_f32 v[176:177], v[176:177], v[172:173]
	v_pk_mul_f32 v[250:251], v[250:251], v[248:249]
	v_pk_mul_f32 v[178:179], v[178:179], v[174:175]
	v_mul_f32_e32 v24, v24, v246
	v_mul_f32_e32 v25, v25, v176
	v_mul_f32_e32 v26, v26, v247
	v_mul_f32_e32 v27, v27, v177
	v_mul_f32_e32 v20, v20, v250
	v_mul_f32_e32 v21, v21, v178
	v_mul_f32_e32 v22, v22, v251
	v_mul_f32_e32 v23, v23, v179
	s_waitcnt vmcnt(2)
	v_lshlrev_b32_e32 v244, 16, v180
	v_lshlrev_b32_e32 v245, 16, v181
	v_and_b32_e32 v180, 0xffff0000, v180
	v_and_b32_e32 v181, 0xffff0000, v181
	v_lshlrev_b32_e32 v246, 16, v184
	v_lshlrev_b32_e32 v247, 16, v185
	v_and_b32_e32 v184, 0xffff0000, v184
	v_and_b32_e32 v185, 0xffff0000, v185
	v_lshlrev_b32_e32 v248, 16, v182
	v_lshlrev_b32_e32 v249, 16, v183
	v_and_b32_e32 v182, 0xffff0000, v182
	v_and_b32_e32 v183, 0xffff0000, v183
	v_lshlrev_b32_e32 v250, 16, v186
	v_lshlrev_b32_e32 v251, 16, v187
	v_and_b32_e32 v186, 0xffff0000, v186
	v_and_b32_e32 v187, 0xffff0000, v187
	v_mul_f32_e32 v244, 0xbfb8aa3b, v244
	v_mul_f32_e32 v245, 0xbfb8aa3b, v245
	v_mul_f32_e32 v180, 0xbfb8aa3b, v180
	v_mul_f32_e32 v181, 0xbfb8aa3b, v181
	v_mul_f32_e32 v246, 0xbfb8aa3b, v246
	v_mul_f32_e32 v247, 0xbfb8aa3b, v247
	v_mul_f32_e32 v184, 0xbfb8aa3b, v184
	v_mul_f32_e32 v185, 0xbfb8aa3b, v185
	v_mul_f32_e32 v248, 0xbfb8aa3b, v248
	v_mul_f32_e32 v249, 0xbfb8aa3b, v249
	v_mul_f32_e32 v182, 0xbfb8aa3b, v182
	v_mul_f32_e32 v183, 0xbfb8aa3b, v183
	v_mul_f32_e32 v250, 0xbfb8aa3b, v250
	v_mul_f32_e32 v251, 0xbfb8aa3b, v251
	v_mul_f32_e32 v186, 0xbfb8aa3b, v186
	v_mul_f32_e32 v187, 0xbfb8aa3b, v187
	v_exp_f32_e32 v244, v244
	v_exp_f32_e32 v245, v245
	v_exp_f32_e32 v180, v180
	v_exp_f32_e32 v181, v181
	v_exp_f32_e32 v246, v246
	v_exp_f32_e32 v247, v247
	v_exp_f32_e32 v184, v184
	v_exp_f32_e32 v185, v185
	v_exp_f32_e32 v248, v248
	v_exp_f32_e32 v249, v249
	v_exp_f32_e32 v182, v182
	v_exp_f32_e32 v183, v183
	v_exp_f32_e32 v250, v250
	v_exp_f32_e32 v251, v251
	v_exp_f32_e32 v186, v186
	v_exp_f32_e32 v187, v187
	v_pk_add_f32 v[244:245], v[244:245], 1.0 op_sel_hi:[1,0]
	v_pk_add_f32 v[180:181], v[180:181], 1.0 op_sel_hi:[1,0]
	v_pk_add_f32 v[246:247], v[246:247], 1.0 op_sel_hi:[1,0]
	v_pk_add_f32 v[184:185], v[184:185], 1.0 op_sel_hi:[1,0]
	v_pk_add_f32 v[248:249], v[248:249], 1.0 op_sel_hi:[1,0]
	v_pk_add_f32 v[182:183], v[182:183], 1.0 op_sel_hi:[1,0]
	v_pk_add_f32 v[250:251], v[250:251], 1.0 op_sel_hi:[1,0]
	v_pk_add_f32 v[186:187], v[186:187], 1.0 op_sel_hi:[1,0]
	v_rcp_f32_e32 v244, v244
	v_rcp_f32_e32 v245, v245
	v_rcp_f32_e32 v180, v180
	v_rcp_f32_e32 v181, v181
	v_rcp_f32_e32 v248, v248
	v_rcp_f32_e32 v249, v249
	v_rcp_f32_e32 v182, v182
	v_rcp_f32_e32 v183, v183
	v_pk_mul_f32 v[246:247], v[246:247], v[244:245]
	v_pk_mul_f32 v[184:185], v[184:185], v[180:181]
	v_pk_mul_f32 v[250:251], v[250:251], v[248:249]
	v_pk_mul_f32 v[186:187], v[186:187], v[182:183]
	v_mul_f32_e32 v16, v16, v246
	v_mul_f32_e32 v17, v17, v184
	v_mul_f32_e32 v18, v18, v247
	v_mul_f32_e32 v19, v19, v185
	v_mul_f32_e32 v12, v12, v250
	v_mul_f32_e32 v13, v13, v186
	v_mul_f32_e32 v14, v14, v251
	v_mul_f32_e32 v15, v15, v187
	s_waitcnt vmcnt(0)
	v_lshlrev_b32_e32 v244, 16, v188
	v_lshlrev_b32_e32 v245, 16, v189
	v_and_b32_e32 v188, 0xffff0000, v188
	v_and_b32_e32 v189, 0xffff0000, v189
	v_lshlrev_b32_e32 v246, 16, v192
	v_lshlrev_b32_e32 v247, 16, v193
	v_and_b32_e32 v192, 0xffff0000, v192
	v_and_b32_e32 v193, 0xffff0000, v193
	v_lshlrev_b32_e32 v248, 16, v190
	v_lshlrev_b32_e32 v249, 16, v191
	v_and_b32_e32 v190, 0xffff0000, v190
	v_and_b32_e32 v191, 0xffff0000, v191
	v_lshlrev_b32_e32 v250, 16, v194
	v_lshlrev_b32_e32 v251, 16, v195
	v_and_b32_e32 v194, 0xffff0000, v194
	v_and_b32_e32 v195, 0xffff0000, v195
	v_mul_f32_e32 v244, 0xbfb8aa3b, v244
	v_mul_f32_e32 v245, 0xbfb8aa3b, v245
	v_mul_f32_e32 v188, 0xbfb8aa3b, v188
	v_mul_f32_e32 v189, 0xbfb8aa3b, v189
	v_mul_f32_e32 v246, 0xbfb8aa3b, v246
	v_mul_f32_e32 v247, 0xbfb8aa3b, v247
	v_mul_f32_e32 v192, 0xbfb8aa3b, v192
	v_mul_f32_e32 v193, 0xbfb8aa3b, v193
	v_mul_f32_e32 v248, 0xbfb8aa3b, v248
	v_mul_f32_e32 v249, 0xbfb8aa3b, v249
	v_mul_f32_e32 v190, 0xbfb8aa3b, v190
	v_mul_f32_e32 v191, 0xbfb8aa3b, v191
	v_mul_f32_e32 v250, 0xbfb8aa3b, v250
	v_mul_f32_e32 v251, 0xbfb8aa3b, v251
	v_mul_f32_e32 v194, 0xbfb8aa3b, v194
	v_mul_f32_e32 v195, 0xbfb8aa3b, v195
	v_exp_f32_e32 v244, v244
	v_exp_f32_e32 v245, v245
	v_exp_f32_e32 v188, v188
	v_exp_f32_e32 v189, v189
	v_exp_f32_e32 v246, v246
	v_exp_f32_e32 v247, v247
	v_exp_f32_e32 v192, v192
	v_exp_f32_e32 v193, v193
	v_exp_f32_e32 v248, v248
	v_exp_f32_e32 v249, v249
	v_exp_f32_e32 v190, v190
	v_exp_f32_e32 v191, v191
	v_exp_f32_e32 v250, v250
	v_exp_f32_e32 v251, v251
	v_exp_f32_e32 v194, v194
	v_exp_f32_e32 v195, v195
	v_pk_add_f32 v[244:245], v[244:245], 1.0 op_sel_hi:[1,0]
	v_pk_add_f32 v[188:189], v[188:189], 1.0 op_sel_hi:[1,0]
	v_pk_add_f32 v[246:247], v[246:247], 1.0 op_sel_hi:[1,0]
	v_pk_add_f32 v[192:193], v[192:193], 1.0 op_sel_hi:[1,0]
	v_pk_add_f32 v[248:249], v[248:249], 1.0 op_sel_hi:[1,0]
	v_pk_add_f32 v[190:191], v[190:191], 1.0 op_sel_hi:[1,0]
	v_pk_add_f32 v[250:251], v[250:251], 1.0 op_sel_hi:[1,0]
	v_pk_add_f32 v[194:195], v[194:195], 1.0 op_sel_hi:[1,0]
	v_rcp_f32_e32 v244, v244
	v_rcp_f32_e32 v245, v245
	v_rcp_f32_e32 v188, v188
	v_rcp_f32_e32 v189, v189
	v_rcp_f32_e32 v248, v248
	v_rcp_f32_e32 v249, v249
	v_rcp_f32_e32 v190, v190
	v_rcp_f32_e32 v191, v191
	v_pk_mul_f32 v[246:247], v[246:247], v[244:245]
	v_pk_mul_f32 v[192:193], v[192:193], v[188:189]
	v_pk_mul_f32 v[250:251], v[250:251], v[248:249]
	v_pk_mul_f32 v[194:195], v[194:195], v[190:191]
	v_mul_f32_e32 v8, v8, v246
	v_mul_f32_e32 v9, v9, v192
	v_mul_f32_e32 v10, v10, v247
	v_mul_f32_e32 v11, v11, v193
	v_mul_f32_e32 v4, v4, v250
	v_mul_f32_e32 v5, v5, v194
	v_mul_f32_e32 v6, v6, v251
	v_mul_f32_e32 v7, v7, v195
